# fused GEMM3+LN1 epilogue: modulation vectors requested before the 4-tile exchange, X and H produced together per row group (no mid-epilogue store drain)
# baseline (speedup 1.0000x reference)
.Lg3ln_nostore:
	s_mul_i32 s8, s37, 0x1e000
	s_add_i32 s8, s8, s23
	s_add_i32 s8, s8, 0x4a00000
	s_add_u32 s54, s0, s8
	s_addc_u32 s55, s1, 0
	s_add_u32 s52, s54, 0x4000
	s_addc_u32 s53, s55, 0
	s_add_u32 s54, s54, 0x3000
	s_addc_u32 s55, s55, 0
	global_load_dwordx4 v[150:153], v146, s[52:53]
	global_load_dwordx4 v[154:157], v146, s[52:53] offset:16
	global_load_dwordx4 v[158:161], v146, s[52:53] offset:512
	global_load_dwordx4 v[162:165], v146, s[52:53] offset:528
	global_load_dwordx4 v[210:213], v146, s[54:55]
	global_load_dwordx4 v[214:217], v146, s[54:55] offset:16
	global_load_dwordx4 v[222:225], v146, s[54:55] offset:512
	global_load_dwordx4 v[226:229], v146, s[54:55] offset:528
	s_waitcnt vmcnt(0)
	s_barrier
	v_or_b32_e32 v218, s91, v230
	v_cmp_eq_u32_e32 vcc, 0, v218
	s_and_saveexec_b64 s[34:35], vcc
	s_cbranch_execz .Lg3ln_joined
	s_lshr_b32 s8, s21, 8
	s_lshl_b32 s9, s37, 5
	s_add_i32 s9, s9, s8
	s_lshl_b32 s9, s9, 2
	s_add_i32 s9, s9, 0x2800
	v_mov_b32_e32 v218, s9
	s_add_u32 s8, s0, 0xee3e000
	s_addc_u32 s9, s1, 0
	v_mov_b32_e32 v219, 1
	v_mov_b32_e32 v221, 0
	global_atomic_add v218, v219, s[8:9]

.Lg3ln_joined:
	s_or_b64 exec, exec, s[34:35]
	s_barrier
	global_load_dwordx4 v[166:169], v0, s[30:31] sc1
	global_load_dwordx4 v[170:173], v0, s[30:31] offset:16 sc1
	s_waitcnt vmcnt(0)
	v_add_f32_e32 v218, v166, v168
	v_add_f32_e32 v219, v170, v172
	v_add_f32_e32 v218, v218, v219
	v_mul_f32_e32 v220, 0x3e800000, v218
	v_sub_f32_e32 v218, v166, v220
	v_mul_f32_e32 v219, v218, v218
	v_sub_f32_e32 v218, v168, v220
	v_fmac_f32_e32 v219, v218, v218
	v_sub_f32_e32 v218, v170, v220
	v_fmac_f32_e32 v219, v218, v218
	v_sub_f32_e32 v218, v172, v220
	v_fmac_f32_e32 v219, v218, v218
	v_add_f32_e32 v218, v167, v169
	v_add_f32_e32 v0, v171, v173
	v_add_f32_e32 v218, v218, v0
	v_fmac_f32_e32 v218, 0x43800000, v219
	v_mov_b32_e32 v0, 0x3727c5ac
	v_fmac_f32_e32 v0, 0x3a800000, v218
	v_rsq_f32_e32 v221, v0
	v_lshlrev_b32_e32 v0, 3, v149
	s_nop 0
	ds_write_b64 v0, v[220:221] offset:9216
	s_waitcnt lgkmcnt(0)
	s_barrier
	v_lshlrev_b32_e32 v0, 3, v147
	ds_read_b64 v[218:219], v0 offset:9216
	s_mov_b32 s0, 0
	s_mov_b32 s1, s71
	s_xor_b64 s[0:1], s[0:1], s[62:63]
	s_add_u32 s34, s0, 0x4a3e000
	s_addc_u32 s35, s1, 0
	v_pk_add_f32 v[150:151], v[150:151], 1.0 op_sel_hi:[1,0]
	v_pk_add_f32 v[152:153], v[152:153], 1.0 op_sel_hi:[1,0]
	v_pk_add_f32 v[154:155], v[154:155], 1.0 op_sel_hi:[1,0]
	v_pk_add_f32 v[156:157], v[156:157], 1.0 op_sel_hi:[1,0]
	v_pk_add_f32 v[158:159], v[158:159], 1.0 op_sel_hi:[1,0]
	v_pk_add_f32 v[160:161], v[160:161], 1.0 op_sel_hi:[1,0]
	v_pk_add_f32 v[162:163], v[162:163], 1.0 op_sel_hi:[1,0]
	v_pk_add_f32 v[164:165], v[164:165], 1.0 op_sel_hi:[1,0]
	s_waitcnt lgkmcnt(0)
	ds_read_b64 v[220:221], v0 offset:9344
	v_pk_add_f32 v[126:127], v[126:127], v[218:219] op_sel_hi:[1,0] neg_lo:[0,1] neg_hi:[0,1]
	v_pk_mul_f32 v[126:127], v[126:127], v[218:219] op_sel:[0,1] op_sel_hi:[1,1]
	v_pk_fma_f32 v[126:127], v[126:127], v[174:175], v[190:191]
	v_pk_add_f32 v[128:129], v[128:129], v[218:219] op_sel_hi:[1,0] neg_lo:[0,1] neg_hi:[0,1]
	v_pk_mul_f32 v[128:129], v[128:129], v[218:219] op_sel:[0,1] op_sel_hi:[1,1]
	v_pk_fma_f32 v[128:129], v[128:129], v[176:177], v[192:193]
	v_pk_add_f32 v[122:123], v[122:123], v[218:219] op_sel_hi:[1,0] neg_lo:[0,1] neg_hi:[0,1]
	v_pk_mul_f32 v[122:123], v[122:123], v[218:219] op_sel:[0,1] op_sel_hi:[1,1]
	v_pk_fma_f32 v[122:123], v[122:123], v[178:179], v[194:195]
	v_pk_add_f32 v[124:125], v[124:125], v[218:219] op_sel_hi:[1,0] neg_lo:[0,1] neg_hi:[0,1]
	v_pk_mul_f32 v[124:125], v[124:125], v[218:219] op_sel:[0,1] op_sel_hi:[1,1]
	v_pk_fma_f32 v[124:125], v[124:125], v[180:181], v[196:197]
	v_pk_add_f32 v[118:119], v[118:119], v[218:219] op_sel_hi:[1,0] neg_lo:[0,1] neg_hi:[0,1]
	v_pk_mul_f32 v[118:119], v[118:119], v[218:219] op_sel:[0,1] op_sel_hi:[1,1]
	v_pk_fma_f32 v[118:119], v[118:119], v[182:183], v[202:203]
	v_pk_add_f32 v[120:121], v[120:121], v[218:219] op_sel_hi:[1,0] neg_lo:[0,1] neg_hi:[0,1]
	v_pk_mul_f32 v[120:121], v[120:121], v[218:219] op_sel:[0,1] op_sel_hi:[1,1]
	v_pk_fma_f32 v[120:121], v[120:121], v[184:185], v[204:205]
	v_pk_add_f32 v[114:115], v[114:115], v[218:219] op_sel_hi:[1,0] neg_lo:[0,1] neg_hi:[0,1]
	v_pk_mul_f32 v[114:115], v[114:115], v[218:219] op_sel:[0,1] op_sel_hi:[1,1]
	v_pk_fma_f32 v[114:115], v[114:115], v[186:187], v[206:207]
	v_pk_add_f32 v[116:117], v[116:117], v[218:219] op_sel_hi:[1,0] neg_lo:[0,1] neg_hi:[0,1]
	v_pk_mul_f32 v[116:117], v[116:117], v[218:219] op_sel:[0,1] op_sel_hi:[1,1]
	v_pk_fma_f32 v[116:117], v[116:117], v[188:189], v[208:209]
	global_store_dwordx4 v144, v[126:129], s[38:39]
	global_store_dwordx4 v144, v[122:125], s[38:39] offset:16
	global_store_dwordx4 v144, v[118:121], s[38:39] offset:512
	global_store_dwordx4 v144, v[114:117], s[38:39] offset:528
	v_pk_fma_f32 v[166:167], v[126:127], v[150:151], v[210:211]
	v_pk_fma_f32 v[168:169], v[128:129], v[152:153], v[212:213]
	v_cvt_pk_bf16_f32 v170, v166, v167
	v_cvt_pk_bf16_f32 v171, v168, v169
	v_pk_fma_f32 v[166:167], v[122:123], v[154:155], v[214:215]
	v_pk_fma_f32 v[168:169], v[124:125], v[156:157], v[216:217]
	v_cvt_pk_bf16_f32 v172, v166, v167
	v_cvt_pk_bf16_f32 v173, v168, v169
	global_store_dwordx4 v145, v[170:173], s[34:35]
	v_pk_fma_f32 v[166:167], v[118:119], v[158:159], v[222:223]
	v_pk_fma_f32 v[168:169], v[120:121], v[160:161], v[224:225]
	v_cvt_pk_bf16_f32 v170, v166, v167
	v_cvt_pk_bf16_f32 v171, v168, v169
	v_pk_fma_f32 v[166:167], v[114:115], v[162:163], v[226:227]
	v_pk_fma_f32 v[168:169], v[116:117], v[164:165], v[228:229]
	v_cvt_pk_bf16_f32 v172, v166, v167
	v_cvt_pk_bf16_f32 v173, v168, v169
	global_store_dwordx4 v145, v[170:173], s[34:35] offset:256
	s_waitcnt lgkmcnt(0)
	ds_read_b64 v[218:219], v0 offset:9472
	v_pk_add_f32 v[110:111], v[110:111], v[220:221] op_sel_hi:[1,0] neg_lo:[0,1] neg_hi:[0,1]
	v_pk_mul_f32 v[110:111], v[110:111], v[220:221] op_sel:[0,1] op_sel_hi:[1,1]
	v_pk_fma_f32 v[110:111], v[110:111], v[174:175], v[190:191]
	v_pk_add_f32 v[112:113], v[112:113], v[220:221] op_sel_hi:[1,0] neg_lo:[0,1] neg_hi:[0,1]
	v_pk_mul_f32 v[112:113], v[112:113], v[220:221] op_sel:[0,1] op_sel_hi:[1,1]
	v_pk_fma_f32 v[112:113], v[112:113], v[176:177], v[192:193]
	v_pk_add_f32 v[106:107], v[106:107], v[220:221] op_sel_hi:[1,0] neg_lo:[0,1] neg_hi:[0,1]
	v_pk_mul_f32 v[106:107], v[106:107], v[220:221] op_sel:[0,1] op_sel_hi:[1,1]
	v_pk_fma_f32 v[106:107], v[106:107], v[178:179], v[194:195]
	v_pk_add_f32 v[108:109], v[108:109], v[220:221] op_sel_hi:[1,0] neg_lo:[0,1] neg_hi:[0,1]
	v_pk_mul_f32 v[108:109], v[108:109], v[220:221] op_sel:[0,1] op_sel_hi:[1,1]
	v_pk_fma_f32 v[108:109], v[108:109], v[180:181], v[196:197]
	v_pk_add_f32 v[102:103], v[102:103], v[220:221] op_sel_hi:[1,0] neg_lo:[0,1] neg_hi:[0,1]
	v_pk_mul_f32 v[102:103], v[102:103], v[220:221] op_sel:[0,1] op_sel_hi:[1,1]
	v_pk_fma_f32 v[102:103], v[102:103], v[182:183], v[202:203]
	v_pk_add_f32 v[104:105], v[104:105], v[220:221] op_sel_hi:[1,0] neg_lo:[0,1] neg_hi:[0,1]
	v_pk_mul_f32 v[104:105], v[104:105], v[220:221] op_sel:[0,1] op_sel_hi:[1,1]
	v_pk_fma_f32 v[104:105], v[104:105], v[184:185], v[204:205]
	v_pk_add_f32 v[98:99], v[98:99], v[220:221] op_sel_hi:[1,0] neg_lo:[0,1] neg_hi:[0,1]
	v_pk_mul_f32 v[98:99], v[98:99], v[220:221] op_sel:[0,1] op_sel_hi:[1,1]
	v_pk_fma_f32 v[98:99], v[98:99], v[186:187], v[206:207]
	v_pk_add_f32 v[100:101], v[100:101], v[220:221] op_sel_hi:[1,0] neg_lo:[0,1] neg_hi:[0,1]
	v_pk_mul_f32 v[100:101], v[100:101], v[220:221] op_sel:[0,1] op_sel_hi:[1,1]
	v_pk_fma_f32 v[100:101], v[100:101], v[188:189], v[208:209]
	v_add_u32_e32 v148, 0x10000, v144
	global_store_dwordx4 v148, v[110:113], s[38:39]
	global_store_dwordx4 v148, v[106:109], s[38:39] offset:16
	global_store_dwordx4 v148, v[102:105], s[38:39] offset:512
	global_store_dwordx4 v148, v[98:101], s[38:39] offset:528
	v_add_u32_e32 v149, 0x8000, v145
	v_pk_fma_f32 v[166:167], v[110:111], v[150:151], v[210:211]
	v_pk_fma_f32 v[168:169], v[112:113], v[152:153], v[212:213]
	v_cvt_pk_bf16_f32 v170, v166, v167
	v_cvt_pk_bf16_f32 v171, v168, v169
	v_pk_fma_f32 v[166:167], v[106:107], v[154:155], v[214:215]
	v_pk_fma_f32 v[168:169], v[108:109], v[156:157], v[216:217]
	v_cvt_pk_bf16_f32 v172, v166, v167
	v_cvt_pk_bf16_f32 v173, v168, v169
	global_store_dwordx4 v149, v[170:173], s[34:35]
	v_pk_fma_f32 v[166:167], v[102:103], v[158:159], v[222:223]
	v_pk_fma_f32 v[168:169], v[104:105], v[160:161], v[224:225]
	v_cvt_pk_bf16_f32 v170, v166, v167
	v_cvt_pk_bf16_f32 v171, v168, v169
	v_pk_fma_f32 v[166:167], v[98:99], v[162:163], v[226:227]
	v_pk_fma_f32 v[168:169], v[100:101], v[164:165], v[228:229]
	v_cvt_pk_bf16_f32 v172, v166, v167
	v_cvt_pk_bf16_f32 v173, v168, v169
	global_store_dwordx4 v149, v[170:173], s[34:35] offset:256
	s_waitcnt lgkmcnt(0)
	ds_read_b64 v[220:221], v0 offset:9600
	v_pk_add_f32 v[94:95], v[94:95], v[218:219] op_sel_hi:[1,0] neg_lo:[0,1] neg_hi:[0,1]
	v_pk_mul_f32 v[94:95], v[94:95], v[218:219] op_sel:[0,1] op_sel_hi:[1,1]
	v_pk_fma_f32 v[94:95], v[94:95], v[174:175], v[190:191]
	v_pk_add_f32 v[96:97], v[96:97], v[218:219] op_sel_hi:[1,0] neg_lo:[0,1] neg_hi:[0,1]
	v_pk_mul_f32 v[96:97], v[96:97], v[218:219] op_sel:[0,1] op_sel_hi:[1,1]
	v_pk_fma_f32 v[96:97], v[96:97], v[176:177], v[192:193]
	v_pk_add_f32 v[90:91], v[90:91], v[218:219] op_sel_hi:[1,0] neg_lo:[0,1] neg_hi:[0,1]
	v_pk_mul_f32 v[90:91], v[90:91], v[218:219] op_sel:[0,1] op_sel_hi:[1,1]
	v_pk_fma_f32 v[90:91], v[90:91], v[178:179], v[194:195]
	v_pk_add_f32 v[92:93], v[92:93], v[218:219] op_sel_hi:[1,0] neg_lo:[0,1] neg_hi:[0,1]
	v_pk_mul_f32 v[92:93], v[92:93], v[218:219] op_sel:[0,1] op_sel_hi:[1,1]
	v_pk_fma_f32 v[92:93], v[92:93], v[180:181], v[196:197]
	v_pk_add_f32 v[86:87], v[86:87], v[218:219] op_sel_hi:[1,0] neg_lo:[0,1] neg_hi:[0,1]
	v_pk_mul_f32 v[86:87], v[86:87], v[218:219] op_sel:[0,1] op_sel_hi:[1,1]
	v_pk_fma_f32 v[86:87], v[86:87], v[182:183], v[202:203]
	v_pk_add_f32 v[88:89], v[88:89], v[218:219] op_sel_hi:[1,0] neg_lo:[0,1] neg_hi:[0,1]
	v_pk_mul_f32 v[88:89], v[88:89], v[218:219] op_sel:[0,1] op_sel_hi:[1,1]
	v_pk_fma_f32 v[88:89], v[88:89], v[184:185], v[204:205]
	v_pk_add_f32 v[82:83], v[82:83], v[218:219] op_sel_hi:[1,0] neg_lo:[0,1] neg_hi:[0,1]
	v_pk_mul_f32 v[82:83], v[82:83], v[218:219] op_sel:[0,1] op_sel_hi:[1,1]
	v_pk_fma_f32 v[82:83], v[82:83], v[186:187], v[206:207]
	v_pk_add_f32 v[84:85], v[84:85], v[218:219] op_sel_hi:[1,0] neg_lo:[0,1] neg_hi:[0,1]
	v_pk_mul_f32 v[84:85], v[84:85], v[218:219] op_sel:[0,1] op_sel_hi:[1,1]
	v_pk_fma_f32 v[84:85], v[84:85], v[188:189], v[208:209]
	v_add_u32_e32 v148, 0x20000, v144
	global_store_dwordx4 v148, v[94:97], s[38:39]
	global_store_dwordx4 v148, v[90:93], s[38:39] offset:16
	global_store_dwordx4 v148, v[86:89], s[38:39] offset:512
	global_store_dwordx4 v148, v[82:85], s[38:39] offset:528
	v_add_u32_e32 v149, 0x10000, v145
	v_pk_fma_f32 v[166:167], v[94:95], v[150:151], v[210:211]
	v_pk_fma_f32 v[168:169], v[96:97], v[152:153], v[212:213]
	v_cvt_pk_bf16_f32 v170, v166, v167
	v_cvt_pk_bf16_f32 v171, v168, v169
	v_pk_fma_f32 v[166:167], v[90:91], v[154:155], v[214:215]
	v_pk_fma_f32 v[168:169], v[92:93], v[156:157], v[216:217]
	v_cvt_pk_bf16_f32 v172, v166, v167
	v_cvt_pk_bf16_f32 v173, v168, v169
	global_store_dwordx4 v149, v[170:173], s[34:35]
	v_pk_fma_f32 v[166:167], v[86:87], v[158:159], v[222:223]
	v_pk_fma_f32 v[168:169], v[88:89], v[160:161], v[224:225]
	v_cvt_pk_bf16_f32 v170, v166, v167
	v_cvt_pk_bf16_f32 v171, v168, v169
	v_pk_fma_f32 v[166:167], v[82:83], v[162:163], v[226:227]
	v_pk_fma_f32 v[168:169], v[84:85], v[164:165], v[228:229]
	v_cvt_pk_bf16_f32 v172, v166, v167
	v_cvt_pk_bf16_f32 v173, v168, v169
	global_store_dwordx4 v149, v[170:173], s[34:35] offset:256
	s_waitcnt lgkmcnt(0)
	ds_read_b64 v[218:219], v0 offset:10240
	v_pk_add_f32 v[78:79], v[78:79], v[220:221] op_sel_hi:[1,0] neg_lo:[0,1] neg_hi:[0,1]
	v_pk_mul_f32 v[78:79], v[78:79], v[220:221] op_sel:[0,1] op_sel_hi:[1,1]
	v_pk_fma_f32 v[78:79], v[78:79], v[174:175], v[190:191]
	v_pk_add_f32 v[80:81], v[80:81], v[220:221] op_sel_hi:[1,0] neg_lo:[0,1] neg_hi:[0,1]
	v_pk_mul_f32 v[80:81], v[80:81], v[220:221] op_sel:[0,1] op_sel_hi:[1,1]
	v_pk_fma_f32 v[80:81], v[80:81], v[176:177], v[192:193]
	v_pk_add_f32 v[74:75], v[74:75], v[220:221] op_sel_hi:[1,0] neg_lo:[0,1] neg_hi:[0,1]
	v_pk_mul_f32 v[74:75], v[74:75], v[220:221] op_sel:[0,1] op_sel_hi:[1,1]
	v_pk_fma_f32 v[74:75], v[74:75], v[178:179], v[194:195]
	v_pk_add_f32 v[76:77], v[76:77], v[220:221] op_sel_hi:[1,0] neg_lo:[0,1] neg_hi:[0,1]
	v_pk_mul_f32 v[76:77], v[76:77], v[220:221] op_sel:[0,1] op_sel_hi:[1,1]
	v_pk_fma_f32 v[76:77], v[76:77], v[180:181], v[196:197]
	v_pk_add_f32 v[70:71], v[70:71], v[220:221] op_sel_hi:[1,0] neg_lo:[0,1] neg_hi:[0,1]
	v_pk_mul_f32 v[70:71], v[70:71], v[220:221] op_sel:[0,1] op_sel_hi:[1,1]
	v_pk_fma_f32 v[70:71], v[70:71], v[182:183], v[202:203]
	v_pk_add_f32 v[72:73], v[72:73], v[220:221] op_sel_hi:[1,0] neg_lo:[0,1] neg_hi:[0,1]
	v_pk_mul_f32 v[72:73], v[72:73], v[220:221] op_sel:[0,1] op_sel_hi:[1,1]
	v_pk_fma_f32 v[72:73], v[72:73], v[184:185], v[204:205]
	v_pk_add_f32 v[66:67], v[66:67], v[220:221] op_sel_hi:[1,0] neg_lo:[0,1] neg_hi:[0,1]
	v_pk_mul_f32 v[66:67], v[66:67], v[220:221] op_sel:[0,1] op_sel_hi:[1,1]
	v_pk_fma_f32 v[66:67], v[66:67], v[186:187], v[206:207]
	v_pk_add_f32 v[68:69], v[68:69], v[220:221] op_sel_hi:[1,0] neg_lo:[0,1] neg_hi:[0,1]
	v_pk_mul_f32 v[68:69], v[68:69], v[220:221] op_sel:[0,1] op_sel_hi:[1,1]
	v_pk_fma_f32 v[68:69], v[68:69], v[188:189], v[208:209]
	v_add_u32_e32 v148, 0x30000, v144
	global_store_dwordx4 v148, v[78:81], s[38:39]
	global_store_dwordx4 v148, v[74:77], s[38:39] offset:16
	global_store_dwordx4 v148, v[70:73], s[38:39] offset:512
	global_store_dwordx4 v148, v[66:69], s[38:39] offset:528
	v_add_u32_e32 v149, 0x18000, v145
	v_pk_fma_f32 v[166:167], v[78:79], v[150:151], v[210:211]
	v_pk_fma_f32 v[168:169], v[80:81], v[152:153], v[212:213]
	v_cvt_pk_bf16_f32 v170, v166, v167
	v_cvt_pk_bf16_f32 v171, v168, v169
	v_pk_fma_f32 v[166:167], v[74:75], v[154:155], v[214:215]
	v_pk_fma_f32 v[168:169], v[76:77], v[156:157], v[216:217]
	v_cvt_pk_bf16_f32 v172, v166, v167
	v_cvt_pk_bf16_f32 v173, v168, v169
	global_store_dwordx4 v149, v[170:173], s[34:35]
	v_pk_fma_f32 v[166:167], v[70:71], v[158:159], v[222:223]
	v_pk_fma_f32 v[168:169], v[72:73], v[160:161], v[224:225]
	v_cvt_pk_bf16_f32 v170, v166, v167
	v_cvt_pk_bf16_f32 v171, v168, v169
	v_pk_fma_f32 v[166:167], v[66:67], v[162:163], v[226:227]
	v_pk_fma_f32 v[168:169], v[68:69], v[164:165], v[228:229]
	v_cvt_pk_bf16_f32 v172, v166, v167
	v_cvt_pk_bf16_f32 v173, v168, v169
	global_store_dwordx4 v149, v[170:173], s[34:35] offset:256
	s_waitcnt lgkmcnt(0)
	ds_read_b64 v[220:221], v0 offset:10368
	v_pk_add_f32 v[62:63], v[62:63], v[218:219] op_sel_hi:[1,0] neg_lo:[0,1] neg_hi:[0,1]
	v_pk_mul_f32 v[62:63], v[62:63], v[218:219] op_sel:[0,1] op_sel_hi:[1,1]
	v_pk_fma_f32 v[62:63], v[62:63], v[174:175], v[190:191]
	v_pk_add_f32 v[64:65], v[64:65], v[218:219] op_sel_hi:[1,0] neg_lo:[0,1] neg_hi:[0,1]
	v_pk_mul_f32 v[64:65], v[64:65], v[218:219] op_sel:[0,1] op_sel_hi:[1,1]
	v_pk_fma_f32 v[64:65], v[64:65], v[176:177], v[192:193]
	v_pk_add_f32 v[58:59], v[58:59], v[218:219] op_sel_hi:[1,0] neg_lo:[0,1] neg_hi:[0,1]
	v_pk_mul_f32 v[58:59], v[58:59], v[218:219] op_sel:[0,1] op_sel_hi:[1,1]
	v_pk_fma_f32 v[58:59], v[58:59], v[178:179], v[194:195]
	v_pk_add_f32 v[60:61], v[60:61], v[218:219] op_sel_hi:[1,0] neg_lo:[0,1] neg_hi:[0,1]
	v_pk_mul_f32 v[60:61], v[60:61], v[218:219] op_sel:[0,1] op_sel_hi:[1,1]
	v_pk_fma_f32 v[60:61], v[60:61], v[180:181], v[196:197]
	v_pk_add_f32 v[54:55], v[54:55], v[218:219] op_sel_hi:[1,0] neg_lo:[0,1] neg_hi:[0,1]
	v_pk_mul_f32 v[54:55], v[54:55], v[218:219] op_sel:[0,1] op_sel_hi:[1,1]
	v_pk_fma_f32 v[54:55], v[54:55], v[182:183], v[202:203]
	v_pk_add_f32 v[56:57], v[56:57], v[218:219] op_sel_hi:[1,0] neg_lo:[0,1] neg_hi:[0,1]
	v_pk_mul_f32 v[56:57], v[56:57], v[218:219] op_sel:[0,1] op_sel_hi:[1,1]
	v_pk_fma_f32 v[56:57], v[56:57], v[184:185], v[204:205]
	v_pk_add_f32 v[50:51], v[50:51], v[218:219] op_sel_hi:[1,0] neg_lo:[0,1] neg_hi:[0,1]
	v_pk_mul_f32 v[50:51], v[50:51], v[218:219] op_sel:[0,1] op_sel_hi:[1,1]
	v_pk_fma_f32 v[50:51], v[50:51], v[186:187], v[206:207]
	v_pk_add_f32 v[52:53], v[52:53], v[218:219] op_sel_hi:[1,0] neg_lo:[0,1] neg_hi:[0,1]
	v_pk_mul_f32 v[52:53], v[52:53], v[218:219] op_sel:[0,1] op_sel_hi:[1,1]
	v_pk_fma_f32 v[52:53], v[52:53], v[188:189], v[208:209]
	v_add_u32_e32 v148, 0x80000, v144
	global_store_dwordx4 v148, v[62:65], s[38:39]
	global_store_dwordx4 v148, v[58:61], s[38:39] offset:16
	global_store_dwordx4 v148, v[54:57], s[38:39] offset:512
	global_store_dwordx4 v148, v[50:53], s[38:39] offset:528
	v_add_u32_e32 v149, 0x40000, v145
	v_pk_fma_f32 v[166:167], v[62:63], v[150:151], v[210:211]
	v_pk_fma_f32 v[168:169], v[64:65], v[152:153], v[212:213]
	v_cvt_pk_bf16_f32 v170, v166, v167
	v_cvt_pk_bf16_f32 v171, v168, v169
	v_pk_fma_f32 v[166:167], v[58:59], v[154:155], v[214:215]
	v_pk_fma_f32 v[168:169], v[60:61], v[156:157], v[216:217]
	v_cvt_pk_bf16_f32 v172, v166, v167
	v_cvt_pk_bf16_f32 v173, v168, v169
	global_store_dwordx4 v149, v[170:173], s[34:35]
	v_pk_fma_f32 v[166:167], v[54:55], v[158:159], v[222:223]
	v_pk_fma_f32 v[168:169], v[56:57], v[160:161], v[224:225]
	v_cvt_pk_bf16_f32 v170, v166, v167
	v_cvt_pk_bf16_f32 v171, v168, v169
	v_pk_fma_f32 v[166:167], v[50:51], v[162:163], v[226:227]
	v_pk_fma_f32 v[168:169], v[52:53], v[164:165], v[228:229]
	v_cvt_pk_bf16_f32 v172, v166, v167
	v_cvt_pk_bf16_f32 v173, v168, v169
	global_store_dwordx4 v149, v[170:173], s[34:35] offset:256
	s_waitcnt lgkmcnt(0)
	ds_read_b64 v[218:219], v0 offset:10496
	v_pk_add_f32 v[46:47], v[46:47], v[220:221] op_sel_hi:[1,0] neg_lo:[0,1] neg_hi:[0,1]
	v_pk_mul_f32 v[46:47], v[46:47], v[220:221] op_sel:[0,1] op_sel_hi:[1,1]
	v_pk_fma_f32 v[46:47], v[46:47], v[174:175], v[190:191]
	v_pk_add_f32 v[48:49], v[48:49], v[220:221] op_sel_hi:[1,0] neg_lo:[0,1] neg_hi:[0,1]
	v_pk_mul_f32 v[48:49], v[48:49], v[220:221] op_sel:[0,1] op_sel_hi:[1,1]
	v_pk_fma_f32 v[48:49], v[48:49], v[176:177], v[192:193]
	v_pk_add_f32 v[42:43], v[42:43], v[220:221] op_sel_hi:[1,0] neg_lo:[0,1] neg_hi:[0,1]
	v_pk_mul_f32 v[42:43], v[42:43], v[220:221] op_sel:[0,1] op_sel_hi:[1,1]
	v_pk_fma_f32 v[42:43], v[42:43], v[178:179], v[194:195]
	v_pk_add_f32 v[44:45], v[44:45], v[220:221] op_sel_hi:[1,0] neg_lo:[0,1] neg_hi:[0,1]
	v_pk_mul_f32 v[44:45], v[44:45], v[220:221] op_sel:[0,1] op_sel_hi:[1,1]
	v_pk_fma_f32 v[44:45], v[44:45], v[180:181], v[196:197]
	v_pk_add_f32 v[38:39], v[38:39], v[220:221] op_sel_hi:[1,0] neg_lo:[0,1] neg_hi:[0,1]
	v_pk_mul_f32 v[38:39], v[38:39], v[220:221] op_sel:[0,1] op_sel_hi:[1,1]
	v_pk_fma_f32 v[38:39], v[38:39], v[182:183], v[202:203]
	v_pk_add_f32 v[40:41], v[40:41], v[220:221] op_sel_hi:[1,0] neg_lo:[0,1] neg_hi:[0,1]
	v_pk_mul_f32 v[40:41], v[40:41], v[220:221] op_sel:[0,1] op_sel_hi:[1,1]
	v_pk_fma_f32 v[40:41], v[40:41], v[184:185], v[204:205]
	v_pk_add_f32 v[34:35], v[34:35], v[220:221] op_sel_hi:[1,0] neg_lo:[0,1] neg_hi:[0,1]
	v_pk_mul_f32 v[34:35], v[34:35], v[220:221] op_sel:[0,1] op_sel_hi:[1,1]
	v_pk_fma_f32 v[34:35], v[34:35], v[186:187], v[206:207]
	v_pk_add_f32 v[36:37], v[36:37], v[220:221] op_sel_hi:[1,0] neg_lo:[0,1] neg_hi:[0,1]
	v_pk_mul_f32 v[36:37], v[36:37], v[220:221] op_sel:[0,1] op_sel_hi:[1,1]
	v_pk_fma_f32 v[36:37], v[36:37], v[188:189], v[208:209]
	v_add_u32_e32 v148, 0x90000, v144
	global_store_dwordx4 v148, v[46:49], s[38:39]
	global_store_dwordx4 v148, v[42:45], s[38:39] offset:16
	global_store_dwordx4 v148, v[38:41], s[38:39] offset:512
	global_store_dwordx4 v148, v[34:37], s[38:39] offset:528
	v_add_u32_e32 v149, 0x48000, v145
	v_pk_fma_f32 v[166:167], v[46:47], v[150:151], v[210:211]
	v_pk_fma_f32 v[168:169], v[48:49], v[152:153], v[212:213]
	v_cvt_pk_bf16_f32 v170, v166, v167
	v_cvt_pk_bf16_f32 v171, v168, v169
	v_pk_fma_f32 v[166:167], v[42:43], v[154:155], v[214:215]
	v_pk_fma_f32 v[168:169], v[44:45], v[156:157], v[216:217]
	v_cvt_pk_bf16_f32 v172, v166, v167
	v_cvt_pk_bf16_f32 v173, v168, v169
	global_store_dwordx4 v149, v[170:173], s[34:35]
	v_pk_fma_f32 v[166:167], v[38:39], v[158:159], v[222:223]
	v_pk_fma_f32 v[168:169], v[40:41], v[160:161], v[224:225]
	v_cvt_pk_bf16_f32 v170, v166, v167
	v_cvt_pk_bf16_f32 v171, v168, v169
	v_pk_fma_f32 v[166:167], v[34:35], v[162:163], v[226:227]
	v_pk_fma_f32 v[168:169], v[36:37], v[164:165], v[228:229]
	v_cvt_pk_bf16_f32 v172, v166, v167
	v_cvt_pk_bf16_f32 v173, v168, v169
	global_store_dwordx4 v149, v[170:173], s[34:35] offset:256
	s_waitcnt lgkmcnt(0)
	ds_read_b64 v[220:221], v0 offset:10624
	v_pk_add_f32 v[30:31], v[30:31], v[218:219] op_sel_hi:[1,0] neg_lo:[0,1] neg_hi:[0,1]
	v_pk_mul_f32 v[30:31], v[30:31], v[218:219] op_sel:[0,1] op_sel_hi:[1,1]
	v_pk_fma_f32 v[30:31], v[30:31], v[174:175], v[190:191]
	v_pk_add_f32 v[32:33], v[32:33], v[218:219] op_sel_hi:[1,0] neg_lo:[0,1] neg_hi:[0,1]
	v_pk_mul_f32 v[32:33], v[32:33], v[218:219] op_sel:[0,1] op_sel_hi:[1,1]
	v_pk_fma_f32 v[32:33], v[32:33], v[176:177], v[192:193]
	v_pk_add_f32 v[26:27], v[26:27], v[218:219] op_sel_hi:[1,0] neg_lo:[0,1] neg_hi:[0,1]
	v_pk_mul_f32 v[26:27], v[26:27], v[218:219] op_sel:[0,1] op_sel_hi:[1,1]
	v_pk_fma_f32 v[26:27], v[26:27], v[178:179], v[194:195]
	v_pk_add_f32 v[28:29], v[28:29], v[218:219] op_sel_hi:[1,0] neg_lo:[0,1] neg_hi:[0,1]
	v_pk_mul_f32 v[28:29], v[28:29], v[218:219] op_sel:[0,1] op_sel_hi:[1,1]
	v_pk_fma_f32 v[28:29], v[28:29], v[180:181], v[196:197]
	v_pk_add_f32 v[22:23], v[22:23], v[218:219] op_sel_hi:[1,0] neg_lo:[0,1] neg_hi:[0,1]
	v_pk_mul_f32 v[22:23], v[22:23], v[218:219] op_sel:[0,1] op_sel_hi:[1,1]
	v_pk_fma_f32 v[22:23], v[22:23], v[182:183], v[202:203]
	v_pk_add_f32 v[24:25], v[24:25], v[218:219] op_sel_hi:[1,0] neg_lo:[0,1] neg_hi:[0,1]
	v_pk_mul_f32 v[24:25], v[24:25], v[218:219] op_sel:[0,1] op_sel_hi:[1,1]
	v_pk_fma_f32 v[24:25], v[24:25], v[184:185], v[204:205]
	v_pk_add_f32 v[18:19], v[18:19], v[218:219] op_sel_hi:[1,0] neg_lo:[0,1] neg_hi:[0,1]
	v_pk_mul_f32 v[18:19], v[18:19], v[218:219] op_sel:[0,1] op_sel_hi:[1,1]
	v_pk_fma_f32 v[18:19], v[18:19], v[186:187], v[206:207]
	v_pk_add_f32 v[20:21], v[20:21], v[218:219] op_sel_hi:[1,0] neg_lo:[0,1] neg_hi:[0,1]
	v_pk_mul_f32 v[20:21], v[20:21], v[218:219] op_sel:[0,1] op_sel_hi:[1,1]
	v_pk_fma_f32 v[20:21], v[20:21], v[188:189], v[208:209]
	v_add_u32_e32 v148, 0xa0000, v144
	global_store_dwordx4 v148, v[30:33], s[38:39]
	global_store_dwordx4 v148, v[26:29], s[38:39] offset:16
	global_store_dwordx4 v148, v[22:25], s[38:39] offset:512
	global_store_dwordx4 v148, v[18:21], s[38:39] offset:528
	v_add_u32_e32 v149, 0x50000, v145
	v_pk_fma_f32 v[166:167], v[30:31], v[150:151], v[210:211]
	v_pk_fma_f32 v[168:169], v[32:33], v[152:153], v[212:213]
	v_cvt_pk_bf16_f32 v170, v166, v167
	v_cvt_pk_bf16_f32 v171, v168, v169
	v_pk_fma_f32 v[166:167], v[26:27], v[154:155], v[214:215]
	v_pk_fma_f32 v[168:169], v[28:29], v[156:157], v[216:217]
	v_cvt_pk_bf16_f32 v172, v166, v167
	v_cvt_pk_bf16_f32 v173, v168, v169
	global_store_dwordx4 v149, v[170:173], s[34:35]
	v_pk_fma_f32 v[166:167], v[22:23], v[158:159], v[222:223]
	v_pk_fma_f32 v[168:169], v[24:25], v[160:161], v[224:225]
	v_cvt_pk_bf16_f32 v170, v166, v167
	v_cvt_pk_bf16_f32 v171, v168, v169
	v_pk_fma_f32 v[166:167], v[18:19], v[162:163], v[226:227]
	v_pk_fma_f32 v[168:169], v[20:21], v[164:165], v[228:229]
	v_cvt_pk_bf16_f32 v172, v166, v167
	v_cvt_pk_bf16_f32 v173, v168, v169
	global_store_dwordx4 v149, v[170:173], s[34:35] offset:256
	s_waitcnt lgkmcnt(0)
	v_pk_add_f32 v[14:15], v[14:15], v[220:221] op_sel_hi:[1,0] neg_lo:[0,1] neg_hi:[0,1]
	v_pk_mul_f32 v[14:15], v[14:15], v[220:221] op_sel:[0,1] op_sel_hi:[1,1]
	v_pk_fma_f32 v[14:15], v[14:15], v[174:175], v[190:191]
	v_pk_add_f32 v[16:17], v[16:17], v[220:221] op_sel_hi:[1,0] neg_lo:[0,1] neg_hi:[0,1]
	v_pk_mul_f32 v[16:17], v[16:17], v[220:221] op_sel:[0,1] op_sel_hi:[1,1]
	v_pk_fma_f32 v[16:17], v[16:17], v[176:177], v[192:193]
	v_pk_add_f32 v[10:11], v[10:11], v[220:221] op_sel_hi:[1,0] neg_lo:[0,1] neg_hi:[0,1]
	v_pk_mul_f32 v[10:11], v[10:11], v[220:221] op_sel:[0,1] op_sel_hi:[1,1]
	v_pk_fma_f32 v[10:11], v[10:11], v[178:179], v[194:195]
	v_pk_add_f32 v[12:13], v[12:13], v[220:221] op_sel_hi:[1,0] neg_lo:[0,1] neg_hi:[0,1]
	v_pk_mul_f32 v[12:13], v[12:13], v[220:221] op_sel:[0,1] op_sel_hi:[1,1]
	v_pk_fma_f32 v[12:13], v[12:13], v[180:181], v[196:197]
	v_pk_add_f32 v[6:7], v[6:7], v[220:221] op_sel_hi:[1,0] neg_lo:[0,1] neg_hi:[0,1]
	v_pk_mul_f32 v[6:7], v[6:7], v[220:221] op_sel:[0,1] op_sel_hi:[1,1]
	v_pk_fma_f32 v[6:7], v[6:7], v[182:183], v[202:203]
	v_pk_add_f32 v[8:9], v[8:9], v[220:221] op_sel_hi:[1,0] neg_lo:[0,1] neg_hi:[0,1]
	v_pk_mul_f32 v[8:9], v[8:9], v[220:221] op_sel:[0,1] op_sel_hi:[1,1]
	v_pk_fma_f32 v[8:9], v[8:9], v[184:185], v[204:205]
	v_pk_add_f32 v[2:3], v[2:3], v[220:221] op_sel_hi:[1,0] neg_lo:[0,1] neg_hi:[0,1]
	v_pk_mul_f32 v[2:3], v[2:3], v[220:221] op_sel:[0,1] op_sel_hi:[1,1]
	v_pk_fma_f32 v[2:3], v[2:3], v[186:187], v[206:207]
	v_pk_add_f32 v[4:5], v[4:5], v[220:221] op_sel_hi:[1,0] neg_lo:[0,1] neg_hi:[0,1]
	v_pk_mul_f32 v[4:5], v[4:5], v[220:221] op_sel:[0,1] op_sel_hi:[1,1]
	v_pk_fma_f32 v[4:5], v[4:5], v[188:189], v[208:209]
	v_add_u32_e32 v148, 0xb0000, v144
	global_store_dwordx4 v148, v[14:17], s[38:39]
	global_store_dwordx4 v148, v[10:13], s[38:39] offset:16
	global_store_dwordx4 v148, v[6:9], s[38:39] offset:512
	global_store_dwordx4 v148, v[2:5], s[38:39] offset:528
	v_add_u32_e32 v149, 0x58000, v145
	v_pk_fma_f32 v[166:167], v[14:15], v[150:151], v[210:211]
	v_pk_fma_f32 v[168:169], v[16:17], v[152:153], v[212:213]
	v_cvt_pk_bf16_f32 v170, v166, v167
	v_cvt_pk_bf16_f32 v171, v168, v169
	v_pk_fma_f32 v[166:167], v[10:11], v[154:155], v[214:215]
	v_pk_fma_f32 v[168:169], v[12:13], v[156:157], v[216:217]
	v_cvt_pk_bf16_f32 v172, v166, v167
	v_cvt_pk_bf16_f32 v173, v168, v169
	global_store_dwordx4 v149, v[170:173], s[34:35]
	v_pk_fma_f32 v[166:167], v[6:7], v[158:159], v[222:223]
	v_pk_fma_f32 v[168:169], v[8:9], v[160:161], v[224:225]
	v_cvt_pk_bf16_f32 v170, v166, v167
	v_cvt_pk_bf16_f32 v171, v168, v169
	v_pk_fma_f32 v[166:167], v[2:3], v[162:163], v[226:227]
	v_pk_fma_f32 v[168:169], v[4:5], v[164:165], v[228:229]
	v_cvt_pk_bf16_f32 v172, v166, v167
	v_cvt_pk_bf16_f32 v173, v168, v169
	global_store_dwordx4 v149, v[170:173], s[34:35] offset:256
	s_andn2_b64 vcc, exec, s[4:5]
	s_mov_b64 s[0:1], -1
	s_cbranch_vccnz .LBB0_809
	s_andn2_b64 vcc, exec, s[10:11]
	s_cbranch_vccnz .LBB0_808
	s_barrier
	s_branch .LBB0_808
